# P1 gates epilogue rewritten: fused scale/bias fma, packed f32 ops, magic-number round+v_perm pack (5.75 instr/elem vs 9.75)
# speedup vs baseline: 1.0193x; 1.0029x over previous
;     __device__ __forceinline__ void operator()(const f32x4 (&acc)[2][2][4][2], const Unit& u, int wr, int wc, int fr, int fq) const {
;     ...
;                 for (int n = 0; n < 2; ++n) bv[bj][n] = *(const f32x4*)(bgate + col0 + bj * HALF + 4 * n);
; #pragma unroll
;             for (int ai = 0; ai < 2; ++ai)
; #pragma unroll
;                 for (int m = 0; m < 4; ++m) { unsigned char* rowp = (unsigned char*)Gt + (size_t)(row0 + ai * HALF + m * 16) * GC + col0;
; #pragma unroll
;                     for (int bj = 0; bj < 2; ++bj) { f32x4 v0 = acc[ai][bj][m][0] * 0.03125f + bv[bj][0], v1 = acc[ai][bj][m][1] * 0.03125f + bv[bj][1];
;                         unsigned q[8];
; #pragma unroll
;                         for (int e = 0; e < 4; ++e) { q[e] = (unsigned)__builtin_rintf(255.f * __builtin_amdgcn_rcpf(1.f + __builtin_amdgcn_exp2f(-LOG2E * v0[e]))); q[4 + e] = (unsigned)__builtin_rintf(255.f * __builtin_amdgcn_rcpf(1.f + __builtin_amdgcn_exp2f(-LOG2E * v1[e]))); }
;                         u32x2g w; w.x = q[0] | (q[1] << 8) | (q[2] << 16) | (q[3] << 24); w.y = q[4] | (q[5] << 8) | (q[6] << 16) | (q[7] << 24);
;                         *(u32x2g*)(rowp + bj * HALF) = w; } }
.LBB0_111:
	s_and_b64 vcc, exec, s[70:71]
	s_cbranch_vccz .LBB0_113
	s_lshl_b32 s0, s13, 8
	v_lshlrev_b32_e32 v146, 3, v130
	s_add_i32 s1, s86, s0
	v_add_u32_e32 v128, s1, v146
	v_ashrrev_i32_e32 v129, 31, v128
	v_lshl_add_u64 v[128:129], v[128:129], 2, s[46:47]
	global_load_dwordx4 v[140:143], v[128:129], off
	global_load_dwordx4 v[136:139], v[128:129], off offset:16
	global_load_dwordx4 v[132:135], v[128:129], off offset:512
	s_nop 0
	global_load_dwordx4 v[128:131], v[128:129], off offset:528
	v_ashrrev_i32_e32 v153, 31, v152
	s_mov_b32 s1, s12
	v_lshlrev_b64 v[148:149], 11, v[152:153]
	v_ashrrev_i32_e32 v147, 31, v146
	s_or_b32 s0, s82, s0
	v_lshl_add_u64 v[148:149], s[42:43], 0, v[148:149]
	v_lshl_add_u64 v[154:155], s[0:1], 0, v[146:147]
	v_lshl_add_u64 v[150:151], v[148:149], 0, v[154:155]
	s_waitcnt vmcnt(0)
	s_mov_b64 s[70:71], 0x8000
	s_mov_b64 s[72:73], 0x10000
	s_mov_b64 s[74:75], 0x18000
	s_mov_b32 s92, 0xbd38aa3b
	s_mov_b32 s93, 0xbd38aa3b
	s_mov_b32 s94, 0x437f0000
	s_mov_b32 s95, 0x437f0000
	s_mov_b32 s96, 1.0
	s_mov_b32 s97, 1.0
	s_mov_b32 s98, 0x0c0c0400
	s_mov_b32 s99, 0x0c040100
	s_mov_b32 s101, 0x04020100
	v_mov_b32_e32 v236, 0x4b000000
	v_mov_b32_e32 v237, 0x4b000000
	v_lshl_add_u64 v[210:211], v[150:151], 0, s[70:71]
	v_lshl_add_u64 v[212:213], v[150:151], 0, s[72:73]
	v_lshl_add_u64 v[214:215], v[150:151], 0, s[74:75]
	v_lshl_add_u64 v[216:217], v[150:151], 0, s[50:51]
	v_lshl_add_u64 v[218:219], v[150:151], 0, s[56:57]
	v_lshl_add_u64 v[220:221], v[150:151], 0, s[58:59]
	v_lshl_add_u64 v[222:223], v[150:151], 0, s[60:61]
	v_mul_f32_e32 v128, 0xbfb8aa3b, v128
	v_mul_f32_e32 v129, 0xbfb8aa3b, v129
	v_mul_f32_e32 v130, 0xbfb8aa3b, v130
	v_mul_f32_e32 v131, 0xbfb8aa3b, v131
	v_mul_f32_e32 v132, 0xbfb8aa3b, v132
	v_mul_f32_e32 v133, 0xbfb8aa3b, v133
	v_mul_f32_e32 v134, 0xbfb8aa3b, v134
	v_mul_f32_e32 v135, 0xbfb8aa3b, v135
	v_mul_f32_e32 v136, 0xbfb8aa3b, v136
	v_mul_f32_e32 v137, 0xbfb8aa3b, v137
	v_mul_f32_e32 v138, 0xbfb8aa3b, v138
	v_mul_f32_e32 v139, 0xbfb8aa3b, v139
	v_mul_f32_e32 v140, 0xbfb8aa3b, v140
	v_mul_f32_e32 v141, 0xbfb8aa3b, v141
	v_mul_f32_e32 v142, 0xbfb8aa3b, v142
	v_mul_f32_e32 v143, 0xbfb8aa3b, v143
	v_pk_fma_f32 v[124:125], v[124:125], s[92:93], v[140:141]
	v_pk_fma_f32 v[126:127], v[126:127], s[92:93], v[142:143]
	v_pk_fma_f32 v[120:121], v[120:121], s[92:93], v[136:137]
	v_pk_fma_f32 v[122:123], v[122:123], s[92:93], v[138:139]
	v_exp_f32_e32 v124, v124
	v_exp_f32_e32 v125, v125
	v_exp_f32_e32 v126, v126
	v_exp_f32_e32 v127, v127
	v_exp_f32_e32 v120, v120
	v_exp_f32_e32 v121, v121
	v_exp_f32_e32 v122, v122
	v_exp_f32_e32 v123, v123
	v_pk_add_f32 v[124:125], v[124:125], s[96:97]
	v_pk_add_f32 v[126:127], v[126:127], s[96:97]
	v_pk_add_f32 v[120:121], v[120:121], s[96:97]
	v_pk_add_f32 v[122:123], v[122:123], s[96:97]
	v_rcp_f32_e32 v124, v124
	v_rcp_f32_e32 v125, v125
	v_rcp_f32_e32 v126, v126
	v_rcp_f32_e32 v127, v127
	v_rcp_f32_e32 v120, v120
	v_rcp_f32_e32 v121, v121
	v_rcp_f32_e32 v122, v122
	v_rcp_f32_e32 v123, v123
	v_pk_fma_f32 v[124:125], v[124:125], s[94:95], v[236:237]
	v_pk_fma_f32 v[126:127], v[126:127], s[94:95], v[236:237]
	v_pk_fma_f32 v[120:121], v[120:121], s[94:95], v[236:237]
	v_pk_fma_f32 v[122:123], v[122:123], s[94:95], v[236:237]
	v_perm_b32 v178, v125, v124, s98
	v_perm_b32 v179, v121, v120, s98
	v_perm_b32 v178, v126, v178, s99
	v_perm_b32 v179, v122, v179, s99
	v_perm_b32 v178, v127, v178, s101
	v_perm_b32 v179, v123, v179, s101
	global_store_dwordx2 v[150:151], v[178:179], off offset:-3072
	v_pk_fma_f32 v[116:117], v[116:117], s[92:93], v[132:133]
	v_pk_fma_f32 v[118:119], v[118:119], s[92:93], v[134:135]
	v_pk_fma_f32 v[112:113], v[112:113], s[92:93], v[128:129]
	v_pk_fma_f32 v[114:115], v[114:115], s[92:93], v[130:131]
	v_exp_f32_e32 v116, v116
	v_exp_f32_e32 v117, v117
	v_exp_f32_e32 v118, v118
	v_exp_f32_e32 v119, v119
	v_exp_f32_e32 v112, v112
	v_exp_f32_e32 v113, v113
	v_exp_f32_e32 v114, v114
	v_exp_f32_e32 v115, v115
	v_pk_add_f32 v[116:117], v[116:117], s[96:97]
	v_pk_add_f32 v[118:119], v[118:119], s[96:97]
	v_pk_add_f32 v[112:113], v[112:113], s[96:97]
	v_pk_add_f32 v[114:115], v[114:115], s[96:97]
	v_rcp_f32_e32 v116, v116
	v_rcp_f32_e32 v117, v117
	v_rcp_f32_e32 v118, v118
	v_rcp_f32_e32 v119, v119
	v_rcp_f32_e32 v112, v112
	v_rcp_f32_e32 v113, v113
	v_rcp_f32_e32 v114, v114
	v_rcp_f32_e32 v115, v115
	v_pk_fma_f32 v[116:117], v[116:117], s[94:95], v[236:237]
	v_pk_fma_f32 v[118:119], v[118:119], s[94:95], v[236:237]
	v_pk_fma_f32 v[112:113], v[112:113], s[94:95], v[236:237]
	v_pk_fma_f32 v[114:115], v[114:115], s[94:95], v[236:237]
	v_perm_b32 v180, v117, v116, s98
	v_perm_b32 v181, v113, v112, s98
	v_perm_b32 v180, v118, v180, s99
	v_perm_b32 v181, v114, v181, s99
	v_perm_b32 v180, v119, v180, s101
	v_perm_b32 v181, v115, v181, s101
	global_store_dwordx2 v[150:151], v[180:181], off offset:-2944
	v_pk_fma_f32 v[108:109], v[108:109], s[92:93], v[140:141]
	v_pk_fma_f32 v[110:111], v[110:111], s[92:93], v[142:143]
	v_pk_fma_f32 v[104:105], v[104:105], s[92:93], v[136:137]
	v_pk_fma_f32 v[106:107], v[106:107], s[92:93], v[138:139]
	v_exp_f32_e32 v108, v108
	v_exp_f32_e32 v109, v109
	v_exp_f32_e32 v110, v110
	v_exp_f32_e32 v111, v111
	v_exp_f32_e32 v104, v104
	v_exp_f32_e32 v105, v105
	v_exp_f32_e32 v106, v106
	v_exp_f32_e32 v107, v107
	v_pk_add_f32 v[108:109], v[108:109], s[96:97]
	v_pk_add_f32 v[110:111], v[110:111], s[96:97]
	v_pk_add_f32 v[104:105], v[104:105], s[96:97]
	v_pk_add_f32 v[106:107], v[106:107], s[96:97]
	v_rcp_f32_e32 v108, v108
	v_rcp_f32_e32 v109, v109
	v_rcp_f32_e32 v110, v110
	v_rcp_f32_e32 v111, v111
	v_rcp_f32_e32 v104, v104
;     __device__ __forceinline__ void operator()(const f32x4 (&acc)[2][2][4][2], const Unit& u, int wr, int wc, int fr, int fq) const {
;     ...
;                 for (int m = 0; m < 4; ++m) { unsigned char* rowp = (unsigned char*)Gt + (size_t)(row0 + ai * HALF + m * 16) * GC + col0;
; #pragma unroll
;                     for (int bj = 0; bj < 2; ++bj) { f32x4 v0 = acc[ai][bj][m][0] * 0.03125f + bv[bj][0], v1 = acc[ai][bj][m][1] * 0.03125f + bv[bj][1];
;                         unsigned q[8];
; #pragma unroll
;                         for (int e = 0; e < 4; ++e) { q[e] = (unsigned)__builtin_rintf(255.f * __builtin_amdgcn_rcpf(1.f + __builtin_amdgcn_exp2f(-LOG2E * v0[e]))); q[4 + e] = (unsigned)__builtin_rintf(255.f * __builtin_amdgcn_rcpf(1.f + __builtin_amdgcn_exp2f(-LOG2E * v1[e]))); }
;                         u32x2g w; w.x = q[0] | (q[1] << 8) | (q[2] << 16) | (q[3] << 24); w.y = q[4] | (q[5] << 8) | (q[6] << 16) | (q[7] << 24);
;                         *(u32x2g*)(rowp + bj * HALF) = w; } }
	v_rcp_f32_e32 v105, v105
	v_rcp_f32_e32 v106, v106
	v_rcp_f32_e32 v107, v107
	v_pk_fma_f32 v[108:109], v[108:109], s[94:95], v[236:237]
	v_pk_fma_f32 v[110:111], v[110:111], s[94:95], v[236:237]
	v_pk_fma_f32 v[104:105], v[104:105], s[94:95], v[236:237]
	v_pk_fma_f32 v[106:107], v[106:107], s[94:95], v[236:237]
	v_perm_b32 v182, v109, v108, s98
	v_perm_b32 v183, v105, v104, s98
	v_perm_b32 v182, v110, v182, s99
	v_perm_b32 v183, v106, v183, s99
	v_perm_b32 v182, v111, v182, s101
	v_perm_b32 v183, v107, v183, s101
	global_store_dwordx2 v[210:211], v[182:183], off offset:-3072
	v_pk_fma_f32 v[100:101], v[100:101], s[92:93], v[132:133]
	v_pk_fma_f32 v[102:103], v[102:103], s[92:93], v[134:135]
	v_pk_fma_f32 v[96:97], v[96:97], s[92:93], v[128:129]
	v_pk_fma_f32 v[98:99], v[98:99], s[92:93], v[130:131]
	v_exp_f32_e32 v100, v100
	v_exp_f32_e32 v101, v101
	v_exp_f32_e32 v102, v102
	v_exp_f32_e32 v103, v103
	v_exp_f32_e32 v96, v96
	v_exp_f32_e32 v97, v97
	v_exp_f32_e32 v98, v98
	v_exp_f32_e32 v99, v99
	v_pk_add_f32 v[100:101], v[100:101], s[96:97]
	v_pk_add_f32 v[102:103], v[102:103], s[96:97]
	v_pk_add_f32 v[96:97], v[96:97], s[96:97]
	v_pk_add_f32 v[98:99], v[98:99], s[96:97]
	v_rcp_f32_e32 v100, v100
	v_rcp_f32_e32 v101, v101
	v_rcp_f32_e32 v102, v102
	v_rcp_f32_e32 v103, v103
	v_rcp_f32_e32 v96, v96
	v_rcp_f32_e32 v97, v97
	v_rcp_f32_e32 v98, v98
	v_rcp_f32_e32 v99, v99
	v_pk_fma_f32 v[100:101], v[100:101], s[94:95], v[236:237]
	v_pk_fma_f32 v[102:103], v[102:103], s[94:95], v[236:237]
	v_pk_fma_f32 v[96:97], v[96:97], s[94:95], v[236:237]
	v_pk_fma_f32 v[98:99], v[98:99], s[94:95], v[236:237]
	v_perm_b32 v184, v101, v100, s98
	v_perm_b32 v185, v97, v96, s98
	v_perm_b32 v184, v102, v184, s99
	v_perm_b32 v185, v98, v185, s99
	v_perm_b32 v184, v103, v184, s101
	v_perm_b32 v185, v99, v185, s101
	global_store_dwordx2 v[210:211], v[184:185], off offset:-2944
	v_pk_fma_f32 v[92:93], v[92:93], s[92:93], v[140:141]
	v_pk_fma_f32 v[94:95], v[94:95], s[92:93], v[142:143]
	v_pk_fma_f32 v[88:89], v[88:89], s[92:93], v[136:137]
	v_pk_fma_f32 v[90:91], v[90:91], s[92:93], v[138:139]
	v_exp_f32_e32 v92, v92
	v_exp_f32_e32 v93, v93
	v_exp_f32_e32 v94, v94
	v_exp_f32_e32 v95, v95
	v_exp_f32_e32 v88, v88
	v_exp_f32_e32 v89, v89
	v_exp_f32_e32 v90, v90
	v_exp_f32_e32 v91, v91
	v_pk_add_f32 v[92:93], v[92:93], s[96:97]
	v_pk_add_f32 v[94:95], v[94:95], s[96:97]
	v_pk_add_f32 v[88:89], v[88:89], s[96:97]
	v_pk_add_f32 v[90:91], v[90:91], s[96:97]
	v_rcp_f32_e32 v92, v92
	v_rcp_f32_e32 v93, v93
	v_rcp_f32_e32 v94, v94
	v_rcp_f32_e32 v95, v95
	v_rcp_f32_e32 v88, v88
	v_rcp_f32_e32 v89, v89
	v_rcp_f32_e32 v90, v90
	v_rcp_f32_e32 v91, v91
	v_pk_fma_f32 v[92:93], v[92:93], s[94:95], v[236:237]
	v_pk_fma_f32 v[94:95], v[94:95], s[94:95], v[236:237]
	v_pk_fma_f32 v[88:89], v[88:89], s[94:95], v[236:237]
	v_pk_fma_f32 v[90:91], v[90:91], s[94:95], v[236:237]
	v_perm_b32 v186, v93, v92, s98
	v_perm_b32 v187, v89, v88, s98
	v_perm_b32 v186, v94, v186, s99
	v_perm_b32 v187, v90, v187, s99
	v_perm_b32 v186, v95, v186, s101
	v_perm_b32 v187, v91, v187, s101
	global_store_dwordx2 v[212:213], v[186:187], off offset:-3072
	v_pk_fma_f32 v[84:85], v[84:85], s[92:93], v[132:133]
	v_pk_fma_f32 v[86:87], v[86:87], s[92:93], v[134:135]
	v_pk_fma_f32 v[80:81], v[80:81], s[92:93], v[128:129]
	v_pk_fma_f32 v[82:83], v[82:83], s[92:93], v[130:131]
	v_exp_f32_e32 v84, v84
	v_exp_f32_e32 v85, v85
	v_exp_f32_e32 v86, v86
	v_exp_f32_e32 v87, v87
	v_exp_f32_e32 v80, v80
	v_exp_f32_e32 v81, v81
	v_exp_f32_e32 v82, v82
	v_exp_f32_e32 v83, v83
	v_pk_add_f32 v[84:85], v[84:85], s[96:97]
	v_pk_add_f32 v[86:87], v[86:87], s[96:97]
	v_pk_add_f32 v[80:81], v[80:81], s[96:97]
	v_pk_add_f32 v[82:83], v[82:83], s[96:97]
	v_rcp_f32_e32 v84, v84
	v_rcp_f32_e32 v85, v85
	v_rcp_f32_e32 v86, v86
	v_rcp_f32_e32 v87, v87
	v_rcp_f32_e32 v80, v80
	v_rcp_f32_e32 v81, v81
	v_rcp_f32_e32 v82, v82
	v_rcp_f32_e32 v83, v83
	v_pk_fma_f32 v[84:85], v[84:85], s[94:95], v[236:237]
	v_pk_fma_f32 v[86:87], v[86:87], s[94:95], v[236:237]
	v_pk_fma_f32 v[80:81], v[80:81], s[94:95], v[236:237]
	v_pk_fma_f32 v[82:83], v[82:83], s[94:95], v[236:237]
	v_perm_b32 v188, v85, v84, s98
	v_perm_b32 v189, v81, v80, s98
	v_perm_b32 v188, v86, v188, s99
	v_perm_b32 v189, v82, v189, s99
	v_perm_b32 v188, v87, v188, s101
	v_perm_b32 v189, v83, v189, s101
	global_store_dwordx2 v[212:213], v[188:189], off offset:-2944
	v_pk_fma_f32 v[76:77], v[76:77], s[92:93], v[140:141]
	v_pk_fma_f32 v[78:79], v[78:79], s[92:93], v[142:143]
	v_pk_fma_f32 v[72:73], v[72:73], s[92:93], v[136:137]
	v_pk_fma_f32 v[74:75], v[74:75], s[92:93], v[138:139]
	v_exp_f32_e32 v76, v76
	v_exp_f32_e32 v77, v77
	v_exp_f32_e32 v78, v78
	v_exp_f32_e32 v79, v79
	v_exp_f32_e32 v72, v72
	v_exp_f32_e32 v73, v73
	v_exp_f32_e32 v74, v74
	v_exp_f32_e32 v75, v75
	v_pk_add_f32 v[76:77], v[76:77], s[96:97]
	v_pk_add_f32 v[78:79], v[78:79], s[96:97]
	v_pk_add_f32 v[72:73], v[72:73], s[96:97]
	v_pk_add_f32 v[74:75], v[74:75], s[96:97]
	v_rcp_f32_e32 v76, v76
	v_rcp_f32_e32 v77, v77
	v_rcp_f32_e32 v78, v78
	v_rcp_f32_e32 v79, v79
	v_rcp_f32_e32 v72, v72
	v_rcp_f32_e32 v73, v73
	v_rcp_f32_e32 v74, v74
	v_rcp_f32_e32 v75, v75
	v_pk_fma_f32 v[76:77], v[76:77], s[94:95], v[236:237]
	v_pk_fma_f32 v[78:79], v[78:79], s[94:95], v[236:237]
	v_pk_fma_f32 v[72:73], v[72:73], s[94:95], v[236:237]
	v_pk_fma_f32 v[74:75], v[74:75], s[94:95], v[236:237]
	v_perm_b32 v190, v77, v76, s98
	v_perm_b32 v191, v73, v72, s98
	v_perm_b32 v190, v78, v190, s99
	v_perm_b32 v191, v74, v191, s99
	v_perm_b32 v190, v79, v190, s101
	v_perm_b32 v191, v75, v191, s101
	global_store_dwordx2 v[214:215], v[190:191], off offset:-3072
;     __device__ __forceinline__ void operator()(const f32x4 (&acc)[2][2][4][2], const Unit& u, int wr, int wc, int fr, int fq) const {
;     ...
;                 for (int m = 0; m < 4; ++m) { unsigned char* rowp = (unsigned char*)Gt + (size_t)(row0 + ai * HALF + m * 16) * GC + col0;
; #pragma unroll
;                     for (int bj = 0; bj < 2; ++bj) { f32x4 v0 = acc[ai][bj][m][0] * 0.03125f + bv[bj][0], v1 = acc[ai][bj][m][1] * 0.03125f + bv[bj][1];
;                         unsigned q[8];
; #pragma unroll
;                         for (int e = 0; e < 4; ++e) { q[e] = (unsigned)__builtin_rintf(255.f * __builtin_amdgcn_rcpf(1.f + __builtin_amdgcn_exp2f(-LOG2E * v0[e]))); q[4 + e] = (unsigned)__builtin_rintf(255.f * __builtin_amdgcn_rcpf(1.f + __builtin_amdgcn_exp2f(-LOG2E * v1[e]))); }
;                         u32x2g w; w.x = q[0] | (q[1] << 8) | (q[2] << 16) | (q[3] << 24); w.y = q[4] | (q[5] << 8) | (q[6] << 16) | (q[7] << 24);
;                         *(u32x2g*)(rowp + bj * HALF) = w; } }
	v_pk_fma_f32 v[68:69], v[68:69], s[92:93], v[132:133]
	v_pk_fma_f32 v[70:71], v[70:71], s[92:93], v[134:135]
	v_pk_fma_f32 v[64:65], v[64:65], s[92:93], v[128:129]
	v_pk_fma_f32 v[66:67], v[66:67], s[92:93], v[130:131]
	v_exp_f32_e32 v68, v68
	v_exp_f32_e32 v69, v69
	v_exp_f32_e32 v70, v70
	v_exp_f32_e32 v71, v71
	v_exp_f32_e32 v64, v64
	v_exp_f32_e32 v65, v65
	v_exp_f32_e32 v66, v66
	v_exp_f32_e32 v67, v67
	v_pk_add_f32 v[68:69], v[68:69], s[96:97]
	v_pk_add_f32 v[70:71], v[70:71], s[96:97]
	v_pk_add_f32 v[64:65], v[64:65], s[96:97]
	v_pk_add_f32 v[66:67], v[66:67], s[96:97]
	v_rcp_f32_e32 v68, v68
	v_rcp_f32_e32 v69, v69
	v_rcp_f32_e32 v70, v70
	v_rcp_f32_e32 v71, v71
	v_rcp_f32_e32 v64, v64
	v_rcp_f32_e32 v65, v65
	v_rcp_f32_e32 v66, v66
	v_rcp_f32_e32 v67, v67
	v_pk_fma_f32 v[68:69], v[68:69], s[94:95], v[236:237]
	v_pk_fma_f32 v[70:71], v[70:71], s[94:95], v[236:237]
	v_pk_fma_f32 v[64:65], v[64:65], s[94:95], v[236:237]
	v_pk_fma_f32 v[66:67], v[66:67], s[94:95], v[236:237]
	v_perm_b32 v192, v69, v68, s98
	v_perm_b32 v193, v65, v64, s98
	v_perm_b32 v192, v70, v192, s99
	v_perm_b32 v193, v66, v193, s99
	v_perm_b32 v192, v71, v192, s101
	v_perm_b32 v193, v67, v193, s101
	global_store_dwordx2 v[214:215], v[192:193], off offset:-2944
	v_pk_fma_f32 v[60:61], v[60:61], s[92:93], v[140:141]
	v_pk_fma_f32 v[62:63], v[62:63], s[92:93], v[142:143]
	v_pk_fma_f32 v[56:57], v[56:57], s[92:93], v[136:137]
	v_pk_fma_f32 v[58:59], v[58:59], s[92:93], v[138:139]
	v_exp_f32_e32 v60, v60
	v_exp_f32_e32 v61, v61
	v_exp_f32_e32 v62, v62
	v_exp_f32_e32 v63, v63
	v_exp_f32_e32 v56, v56
	v_exp_f32_e32 v57, v57
	v_exp_f32_e32 v58, v58
	v_exp_f32_e32 v59, v59
	v_pk_add_f32 v[60:61], v[60:61], s[96:97]
	v_pk_add_f32 v[62:63], v[62:63], s[96:97]
	v_pk_add_f32 v[56:57], v[56:57], s[96:97]
	v_pk_add_f32 v[58:59], v[58:59], s[96:97]
	v_rcp_f32_e32 v60, v60
	v_rcp_f32_e32 v61, v61
	v_rcp_f32_e32 v62, v62
	v_rcp_f32_e32 v63, v63
	v_rcp_f32_e32 v56, v56
	v_rcp_f32_e32 v57, v57
	v_rcp_f32_e32 v58, v58
	v_rcp_f32_e32 v59, v59
	v_pk_fma_f32 v[60:61], v[60:61], s[94:95], v[236:237]
	v_pk_fma_f32 v[62:63], v[62:63], s[94:95], v[236:237]
	v_pk_fma_f32 v[56:57], v[56:57], s[94:95], v[236:237]
	v_pk_fma_f32 v[58:59], v[58:59], s[94:95], v[236:237]
	v_perm_b32 v194, v61, v60, s98
	v_perm_b32 v195, v57, v56, s98
	v_perm_b32 v194, v62, v194, s99
	v_perm_b32 v195, v58, v195, s99
	v_perm_b32 v194, v63, v194, s101
	v_perm_b32 v195, v59, v195, s101
	global_store_dwordx2 v[216:217], v[194:195], off offset:-3072
	v_pk_fma_f32 v[52:53], v[52:53], s[92:93], v[132:133]
	v_pk_fma_f32 v[54:55], v[54:55], s[92:93], v[134:135]
	v_pk_fma_f32 v[48:49], v[48:49], s[92:93], v[128:129]
	v_pk_fma_f32 v[50:51], v[50:51], s[92:93], v[130:131]
	v_exp_f32_e32 v52, v52
	v_exp_f32_e32 v53, v53
	v_exp_f32_e32 v54, v54
	v_exp_f32_e32 v55, v55
	v_exp_f32_e32 v48, v48
	v_exp_f32_e32 v49, v49
	v_exp_f32_e32 v50, v50
	v_exp_f32_e32 v51, v51
	v_pk_add_f32 v[52:53], v[52:53], s[96:97]
	v_pk_add_f32 v[54:55], v[54:55], s[96:97]
	v_pk_add_f32 v[48:49], v[48:49], s[96:97]
	v_pk_add_f32 v[50:51], v[50:51], s[96:97]
	v_rcp_f32_e32 v52, v52
	v_rcp_f32_e32 v53, v53
	v_rcp_f32_e32 v54, v54
	v_rcp_f32_e32 v55, v55
	v_rcp_f32_e32 v48, v48
	v_rcp_f32_e32 v49, v49
	v_rcp_f32_e32 v50, v50
	v_rcp_f32_e32 v51, v51
	v_pk_fma_f32 v[52:53], v[52:53], s[94:95], v[236:237]
	v_pk_fma_f32 v[54:55], v[54:55], s[94:95], v[236:237]
	v_pk_fma_f32 v[48:49], v[48:49], s[94:95], v[236:237]
	v_pk_fma_f32 v[50:51], v[50:51], s[94:95], v[236:237]
	v_perm_b32 v196, v53, v52, s98
	v_perm_b32 v197, v49, v48, s98
	v_perm_b32 v196, v54, v196, s99
	v_perm_b32 v197, v50, v197, s99
	v_perm_b32 v196, v55, v196, s101
	v_perm_b32 v197, v51, v197, s101
	global_store_dwordx2 v[216:217], v[196:197], off offset:-2944
	v_pk_fma_f32 v[44:45], v[44:45], s[92:93], v[140:141]
	v_pk_fma_f32 v[46:47], v[46:47], s[92:93], v[142:143]
	v_pk_fma_f32 v[40:41], v[40:41], s[92:93], v[136:137]
	v_pk_fma_f32 v[42:43], v[42:43], s[92:93], v[138:139]
	v_exp_f32_e32 v44, v44
	v_exp_f32_e32 v45, v45
	v_exp_f32_e32 v46, v46
	v_exp_f32_e32 v47, v47
	v_exp_f32_e32 v40, v40
	v_exp_f32_e32 v41, v41
	v_exp_f32_e32 v42, v42
	v_exp_f32_e32 v43, v43
	v_pk_add_f32 v[44:45], v[44:45], s[96:97]
	v_pk_add_f32 v[46:47], v[46:47], s[96:97]
	v_pk_add_f32 v[40:41], v[40:41], s[96:97]
	v_pk_add_f32 v[42:43], v[42:43], s[96:97]
	v_rcp_f32_e32 v44, v44
	v_rcp_f32_e32 v45, v45
	v_rcp_f32_e32 v46, v46
	v_rcp_f32_e32 v47, v47
	v_rcp_f32_e32 v40, v40
	v_rcp_f32_e32 v41, v41
	v_rcp_f32_e32 v42, v42
	v_rcp_f32_e32 v43, v43
	v_pk_fma_f32 v[44:45], v[44:45], s[94:95], v[236:237]
	v_pk_fma_f32 v[46:47], v[46:47], s[94:95], v[236:237]
	v_pk_fma_f32 v[40:41], v[40:41], s[94:95], v[236:237]
	v_pk_fma_f32 v[42:43], v[42:43], s[94:95], v[236:237]
	v_perm_b32 v198, v45, v44, s98
	v_perm_b32 v199, v41, v40, s98
	v_perm_b32 v198, v46, v198, s99
	v_perm_b32 v199, v42, v199, s99
	v_perm_b32 v198, v47, v198, s101
	v_perm_b32 v199, v43, v199, s101
	global_store_dwordx2 v[218:219], v[198:199], off offset:-3072
	v_pk_fma_f32 v[36:37], v[36:37], s[92:93], v[132:133]
	v_pk_fma_f32 v[38:39], v[38:39], s[92:93], v[134:135]
	v_pk_fma_f32 v[32:33], v[32:33], s[92:93], v[128:129]
	v_pk_fma_f32 v[34:35], v[34:35], s[92:93], v[130:131]
	v_exp_f32_e32 v36, v36
	v_exp_f32_e32 v37, v37
	v_exp_f32_e32 v38, v38
	v_exp_f32_e32 v39, v39
	v_exp_f32_e32 v32, v32
	v_exp_f32_e32 v33, v33
	v_exp_f32_e32 v34, v34
	v_exp_f32_e32 v35, v35
	v_pk_add_f32 v[36:37], v[36:37], s[96:97]
	v_pk_add_f32 v[38:39], v[38:39], s[96:97]
	v_pk_add_f32 v[32:33], v[32:33], s[96:97]
	v_pk_add_f32 v[34:35], v[34:35], s[96:97]
;     __device__ __forceinline__ void operator()(const f32x4 (&acc)[2][2][4][2], const Unit& u, int wr, int wc, int fr, int fq) const {
;     ...
;                 for (int m = 0; m < 4; ++m) { unsigned char* rowp = (unsigned char*)Gt + (size_t)(row0 + ai * HALF + m * 16) * GC + col0;
; #pragma unroll
;                     for (int bj = 0; bj < 2; ++bj) { f32x4 v0 = acc[ai][bj][m][0] * 0.03125f + bv[bj][0], v1 = acc[ai][bj][m][1] * 0.03125f + bv[bj][1];
;                         unsigned q[8];
; #pragma unroll
;                         for (int e = 0; e < 4; ++e) { q[e] = (unsigned)__builtin_rintf(255.f * __builtin_amdgcn_rcpf(1.f + __builtin_amdgcn_exp2f(-LOG2E * v0[e]))); q[4 + e] = (unsigned)__builtin_rintf(255.f * __builtin_amdgcn_rcpf(1.f + __builtin_amdgcn_exp2f(-LOG2E * v1[e]))); }
;                         u32x2g w; w.x = q[0] | (q[1] << 8) | (q[2] << 16) | (q[3] << 24); w.y = q[4] | (q[5] << 8) | (q[6] << 16) | (q[7] << 24);
;                         *(u32x2g*)(rowp + bj * HALF) = w; } }
	v_rcp_f32_e32 v36, v36
	v_rcp_f32_e32 v37, v37
	v_rcp_f32_e32 v38, v38
	v_rcp_f32_e32 v39, v39
	v_rcp_f32_e32 v32, v32
	v_rcp_f32_e32 v33, v33
	v_rcp_f32_e32 v34, v34
	v_rcp_f32_e32 v35, v35
	v_pk_fma_f32 v[36:37], v[36:37], s[94:95], v[236:237]
	v_pk_fma_f32 v[38:39], v[38:39], s[94:95], v[236:237]
	v_pk_fma_f32 v[32:33], v[32:33], s[94:95], v[236:237]
	v_pk_fma_f32 v[34:35], v[34:35], s[94:95], v[236:237]
	v_perm_b32 v200, v37, v36, s98
	v_perm_b32 v201, v33, v32, s98
	v_perm_b32 v200, v38, v200, s99
	v_perm_b32 v201, v34, v201, s99
	v_perm_b32 v200, v39, v200, s101
	v_perm_b32 v201, v35, v201, s101
	global_store_dwordx2 v[218:219], v[200:201], off offset:-2944
	v_pk_fma_f32 v[28:29], v[28:29], s[92:93], v[140:141]
	v_pk_fma_f32 v[30:31], v[30:31], s[92:93], v[142:143]
	v_pk_fma_f32 v[24:25], v[24:25], s[92:93], v[136:137]
	v_pk_fma_f32 v[26:27], v[26:27], s[92:93], v[138:139]
	v_exp_f32_e32 v28, v28
	v_exp_f32_e32 v29, v29
	v_exp_f32_e32 v30, v30
	v_exp_f32_e32 v31, v31
	v_exp_f32_e32 v24, v24
	v_exp_f32_e32 v25, v25
	v_exp_f32_e32 v26, v26
	v_exp_f32_e32 v27, v27
	v_pk_add_f32 v[28:29], v[28:29], s[96:97]
	v_pk_add_f32 v[30:31], v[30:31], s[96:97]
	v_pk_add_f32 v[24:25], v[24:25], s[96:97]
	v_pk_add_f32 v[26:27], v[26:27], s[96:97]
	v_rcp_f32_e32 v28, v28
	v_rcp_f32_e32 v29, v29
	v_rcp_f32_e32 v30, v30
	v_rcp_f32_e32 v31, v31
	v_rcp_f32_e32 v24, v24
	v_rcp_f32_e32 v25, v25
	v_rcp_f32_e32 v26, v26
	v_rcp_f32_e32 v27, v27
	v_pk_fma_f32 v[28:29], v[28:29], s[94:95], v[236:237]
	v_pk_fma_f32 v[30:31], v[30:31], s[94:95], v[236:237]
	v_pk_fma_f32 v[24:25], v[24:25], s[94:95], v[236:237]
	v_pk_fma_f32 v[26:27], v[26:27], s[94:95], v[236:237]
	v_perm_b32 v202, v29, v28, s98
	v_perm_b32 v203, v25, v24, s98
	v_perm_b32 v202, v30, v202, s99
	v_perm_b32 v203, v26, v203, s99
	v_perm_b32 v202, v31, v202, s101
	v_perm_b32 v203, v27, v203, s101
	global_store_dwordx2 v[220:221], v[202:203], off offset:-3072
	v_pk_fma_f32 v[20:21], v[20:21], s[92:93], v[132:133]
	v_pk_fma_f32 v[22:23], v[22:23], s[92:93], v[134:135]
	v_pk_fma_f32 v[16:17], v[16:17], s[92:93], v[128:129]
	v_pk_fma_f32 v[18:19], v[18:19], s[92:93], v[130:131]
	v_exp_f32_e32 v20, v20
	v_exp_f32_e32 v21, v21
	v_exp_f32_e32 v22, v22
	v_exp_f32_e32 v23, v23
	v_exp_f32_e32 v16, v16
	v_exp_f32_e32 v17, v17
	v_exp_f32_e32 v18, v18
	v_exp_f32_e32 v19, v19
	v_pk_add_f32 v[20:21], v[20:21], s[96:97]
	v_pk_add_f32 v[22:23], v[22:23], s[96:97]
	v_pk_add_f32 v[16:17], v[16:17], s[96:97]
	v_pk_add_f32 v[18:19], v[18:19], s[96:97]
	v_rcp_f32_e32 v20, v20
	v_rcp_f32_e32 v21, v21
	v_rcp_f32_e32 v22, v22
	v_rcp_f32_e32 v23, v23
	v_rcp_f32_e32 v16, v16
	v_rcp_f32_e32 v17, v17
	v_rcp_f32_e32 v18, v18
	v_rcp_f32_e32 v19, v19
	v_pk_fma_f32 v[20:21], v[20:21], s[94:95], v[236:237]
	v_pk_fma_f32 v[22:23], v[22:23], s[94:95], v[236:237]
	v_pk_fma_f32 v[16:17], v[16:17], s[94:95], v[236:237]
	v_pk_fma_f32 v[18:19], v[18:19], s[94:95], v[236:237]
	v_perm_b32 v204, v21, v20, s98
	v_perm_b32 v205, v17, v16, s98
	v_perm_b32 v204, v22, v204, s99
	v_perm_b32 v205, v18, v205, s99
	v_perm_b32 v204, v23, v204, s101
	v_perm_b32 v205, v19, v205, s101
	global_store_dwordx2 v[220:221], v[204:205], off offset:-2944
	v_pk_fma_f32 v[12:13], v[12:13], s[92:93], v[140:141]
	v_pk_fma_f32 v[14:15], v[14:15], s[92:93], v[142:143]
	v_pk_fma_f32 v[8:9], v[8:9], s[92:93], v[136:137]
	v_pk_fma_f32 v[10:11], v[10:11], s[92:93], v[138:139]
	v_exp_f32_e32 v12, v12
	v_exp_f32_e32 v13, v13
	v_exp_f32_e32 v14, v14
	v_exp_f32_e32 v15, v15
	v_exp_f32_e32 v8, v8
	v_exp_f32_e32 v9, v9
	v_exp_f32_e32 v10, v10
	v_exp_f32_e32 v11, v11
	v_pk_add_f32 v[12:13], v[12:13], s[96:97]
	v_pk_add_f32 v[14:15], v[14:15], s[96:97]
	v_pk_add_f32 v[8:9], v[8:9], s[96:97]
	v_pk_add_f32 v[10:11], v[10:11], s[96:97]
	v_rcp_f32_e32 v12, v12
	v_rcp_f32_e32 v13, v13
	v_rcp_f32_e32 v14, v14
	v_rcp_f32_e32 v15, v15
	v_rcp_f32_e32 v8, v8
	v_rcp_f32_e32 v9, v9
	v_rcp_f32_e32 v10, v10
	v_rcp_f32_e32 v11, v11
	v_pk_fma_f32 v[12:13], v[12:13], s[94:95], v[236:237]
	v_pk_fma_f32 v[14:15], v[14:15], s[94:95], v[236:237]
	v_pk_fma_f32 v[8:9], v[8:9], s[94:95], v[236:237]
	v_pk_fma_f32 v[10:11], v[10:11], s[94:95], v[236:237]
	v_perm_b32 v206, v13, v12, s98
	v_perm_b32 v207, v9, v8, s98
	v_perm_b32 v206, v14, v206, s99
	v_perm_b32 v207, v10, v207, s99
	v_perm_b32 v206, v15, v206, s101
	v_perm_b32 v207, v11, v207, s101
	global_store_dwordx2 v[222:223], v[206:207], off offset:-3072
	v_pk_fma_f32 v[4:5], v[4:5], s[92:93], v[132:133]
	v_pk_fma_f32 v[6:7], v[6:7], s[92:93], v[134:135]
	v_pk_fma_f32 v[0:1], v[0:1], s[92:93], v[128:129]
	v_pk_fma_f32 v[2:3], v[2:3], s[92:93], v[130:131]
	v_exp_f32_e32 v4, v4
	v_exp_f32_e32 v5, v5
	v_exp_f32_e32 v6, v6
	v_exp_f32_e32 v7, v7
	v_exp_f32_e32 v0, v0
	v_exp_f32_e32 v1, v1
	v_exp_f32_e32 v2, v2
	v_exp_f32_e32 v3, v3
	v_pk_add_f32 v[4:5], v[4:5], s[96:97]
	v_pk_add_f32 v[6:7], v[6:7], s[96:97]
	v_pk_add_f32 v[0:1], v[0:1], s[96:97]
	v_pk_add_f32 v[2:3], v[2:3], s[96:97]
	v_rcp_f32_e32 v4, v4
	v_rcp_f32_e32 v5, v5
	v_rcp_f32_e32 v6, v6
	v_rcp_f32_e32 v7, v7
	v_rcp_f32_e32 v0, v0
	v_rcp_f32_e32 v1, v1
	v_rcp_f32_e32 v2, v2
	v_rcp_f32_e32 v3, v3
	v_pk_fma_f32 v[4:5], v[4:5], s[94:95], v[236:237]
	v_pk_fma_f32 v[6:7], v[6:7], s[94:95], v[236:237]
	v_pk_fma_f32 v[0:1], v[0:1], s[94:95], v[236:237]
	v_pk_fma_f32 v[2:3], v[2:3], s[94:95], v[236:237]
	v_perm_b32 v208, v5, v4, s98
	v_perm_b32 v209, v1, v0, s98
	v_perm_b32 v208, v6, v208, s99
	v_perm_b32 v209, v2, v209, s99
	v_perm_b32 v208, v7, v208, s101
	v_perm_b32 v209, v3, v209, s101
	global_store_dwordx2 v[222:223], v[208:209], off offset:-2944
